# v008 + out-proj tail (128x128) tile epilogue with all x loads issued up front
# baseline (speedup 1.0000x reference)
.LBB0_876:
	s_load_dwordx2 s[76:77], s[78:79], 0x0
	s_load_dwordx4 s[8:11], s[90:91], 0xc0
	s_mulk_i32 s97, 0x3000
	v_mov_b32_e32 v35, v33
	s_waitcnt lgkmcnt(0)
	s_add_u32 s72, s76, s72
	s_addc_u32 s73, s77, s73
	s_lshl_b64 s[74:75], s[74:75], 2
	s_add_u32 s76, s10, s74
	s_addc_u32 s77, s11, s75
	s_add_i32 s4, s96, s88
	s_add_i32 s78, s97, 0x100
	s_lshl_b64 s[74:75], s[4:5], 2
	s_add_u32 s74, s76, s74
	s_addc_u32 s75, s77, s75
	v_lshl_add_u64 v[36:37], s[74:75], 0, v[34:35]
	v_add_u32_e32 v32, s4, v43
	v_add_co_u32_e32 v48, vcc, s95, v36
	v_lshlrev_b64 v[52:53], 2, v[32:33]
	s_nop 0
	v_addc_co_u32_e32 v49, vcc, 0, v37, vcc
	v_add_u32_e32 v72, s4, v43
	v_add_u32_e32 v73, s4, v44
	v_add_u32_e32 v74, s4, v45
	v_add_u32_e32 v75, s4, v46
	v_lshlrev_b32_e32 v72, 2, v72
	v_lshlrev_b32_e32 v73, 2, v73
	v_lshlrev_b32_e32 v74, 2, v74
	v_lshlrev_b32_e32 v75, 2, v75
	s_add_u32 s80, s72, 0x20000
	s_addc_u32 s81, s73, 0
	s_add_u32 s100, s70, 0x20000
	s_addc_u32 s101, s71, 0
	global_load_dwordx4 v[48:51], v[48:49], off
	global_load_dwordx4 v[76:79], v72, s[72:73]
	global_load_dwordx4 v[80:83], v73, s[72:73]
	global_load_dwordx4 v[84:87], v74, s[72:73]
	global_load_dwordx4 v[88:91], v75, s[72:73]
	global_load_dwordx4 v[92:95], v72, s[80:81]
	global_load_dwordx4 v[96:99], v73, s[80:81]
	global_load_dwordx4 v[100:103], v74, s[80:81]
	global_load_dwordx4 v[104:107], v75, s[80:81]
	v_add3_u32 v54, s78, v40, v42
	v_add3_u32 v35, s78, v186, v41
	ds_write_b32 v54, v16
	ds_write_b32 v54, v17 offset:272
	ds_write_b32 v54, v18 offset:544
	ds_write_b32 v54, v19 offset:816
	ds_write_b32 v54, v20 offset:2176
	ds_write_b32 v54, v21 offset:2448
	ds_write_b32 v54, v22 offset:2720
	ds_write_b32 v54, v23 offset:2992
	ds_write_b32 v54, v24 offset:4352
	ds_write_b32 v54, v25 offset:4624
	ds_write_b32 v54, v26 offset:4896
	ds_write_b32 v54, v27 offset:5168
	ds_write_b32 v54, v28 offset:6528
	ds_write_b32 v54, v29 offset:6800
	ds_write_b32 v54, v30 offset:7072
	ds_write_b32 v54, v31 offset:7344
	ds_read_b128 v[108:111], v35
	ds_read_b128 v[112:115], v35 offset:2176
	ds_read_b128 v[116:119], v35 offset:4352
	ds_read_b128 v[120:123], v35 offset:6528
	s_waitcnt vmcnt(7) lgkmcnt(3)
	v_pk_fma_f32 v[78:79], v[50:51], v[110:111], v[78:79]
	v_pk_fma_f32 v[76:77], v[48:49], v[108:109], v[76:77]
	global_store_dwordx4 v72, v[76:79], s[70:71]
	s_waitcnt vmcnt(7) lgkmcnt(2)
	v_pk_fma_f32 v[82:83], v[50:51], v[114:115], v[82:83]
	v_pk_fma_f32 v[80:81], v[48:49], v[112:113], v[80:81]
	global_store_dwordx4 v73, v[80:83], s[70:71]
	s_waitcnt vmcnt(7) lgkmcnt(1)
	v_pk_fma_f32 v[86:87], v[50:51], v[118:119], v[86:87]
	v_pk_fma_f32 v[84:85], v[48:49], v[116:117], v[84:85]
	global_store_dwordx4 v74, v[84:87], s[70:71]
	s_waitcnt vmcnt(7) lgkmcnt(0)
	v_pk_fma_f32 v[90:91], v[50:51], v[122:123], v[90:91]
	v_pk_fma_f32 v[88:89], v[48:49], v[120:121], v[88:89]
	global_store_dwordx4 v75, v[88:91], s[70:71]
	ds_write_b32 v54, v0
	ds_write_b32 v54, v1 offset:272
	ds_write_b32 v54, v2 offset:544
	ds_write_b32 v54, v3 offset:816
	ds_write_b32 v54, v4 offset:2176
	ds_write_b32 v54, v5 offset:2448
	ds_write_b32 v54, v6 offset:2720
	ds_write_b32 v54, v7 offset:2992
	ds_write_b32 v54, v8 offset:4352
	ds_write_b32 v54, v9 offset:4624
	ds_write_b32 v54, v10 offset:4896
	ds_write_b32 v54, v11 offset:5168
	ds_write_b32 v54, v12 offset:6528
	ds_write_b32 v54, v13 offset:6800
	ds_write_b32 v54, v14 offset:7072
	ds_write_b32 v54, v15 offset:7344
	ds_read_b128 v[108:111], v35
	ds_read_b128 v[112:115], v35 offset:2176
	ds_read_b128 v[116:119], v35 offset:4352
	ds_read_b128 v[120:123], v35 offset:6528
	s_waitcnt vmcnt(7) lgkmcnt(3)
	v_pk_fma_f32 v[94:95], v[50:51], v[110:111], v[94:95]
	v_pk_fma_f32 v[92:93], v[48:49], v[108:109], v[92:93]
	global_store_dwordx4 v72, v[92:95], s[100:101]
	s_waitcnt vmcnt(7) lgkmcnt(2)
	v_pk_fma_f32 v[98:99], v[50:51], v[114:115], v[98:99]
	v_pk_fma_f32 v[96:97], v[48:49], v[112:113], v[96:97]
	global_store_dwordx4 v73, v[96:99], s[100:101]
	s_waitcnt vmcnt(7) lgkmcnt(1)
	v_pk_fma_f32 v[102:103], v[50:51], v[118:119], v[102:103]
	v_pk_fma_f32 v[100:101], v[48:49], v[116:117], v[100:101]
	global_store_dwordx4 v74, v[100:103], s[100:101]
	s_waitcnt vmcnt(7) lgkmcnt(0)
	v_pk_fma_f32 v[106:107], v[50:51], v[122:123], v[106:107]
	v_pk_fma_f32 v[104:105], v[48:49], v[120:121], v[104:105]
	global_store_dwordx4 v75, v[104:107], s[100:101]
	s_add_i32 s2, s2, s86
	s_add_i32 s93, s93, s94
	s_cmp_lt_i32 s2, s33
	s_barrier
	s_cbranch_scc0 .LBB0_880

	.amdhsa_kernel _Z11mega_kernel6Params
		.amdhsa_group_segment_fixed_size 49408
		.amdhsa_private_segment_fixed_size 0
		.amdhsa_kernarg_size 464
		.amdhsa_user_sgpr_count 2
		.amdhsa_user_sgpr_dispatch_ptr 0
		.amdhsa_user_sgpr_queue_ptr 0
		.amdhsa_user_sgpr_kernarg_segment_ptr 1
		.amdhsa_user_sgpr_dispatch_id 0
		.amdhsa_user_sgpr_kernarg_preload_length 0
		.amdhsa_user_sgpr_kernarg_preload_offset 0
		.amdhsa_user_sgpr_private_segment_size 0
		.amdhsa_uses_dynamic_stack 0
		.amdhsa_enable_private_segment 0
		.amdhsa_system_sgpr_workgroup_id_x 1
		.amdhsa_system_sgpr_workgroup_id_y 1
		.amdhsa_system_sgpr_workgroup_id_z 1
		.amdhsa_system_sgpr_workgroup_info 0
		.amdhsa_system_vgpr_workitem_id 2
		.amdhsa_next_free_vgpr 248
		.amdhsa_next_free_sgpr 102
		.amdhsa_accum_offset 248
		.amdhsa_reserve_vcc 1
		.amdhsa_float_round_mode_32 0
		.amdhsa_float_round_mode_16_64 0
		.amdhsa_float_denorm_mode_32 3
		.amdhsa_float_denorm_mode_16_64 3
		.amdhsa_dx10_clamp 1
		.amdhsa_ieee_mode 1
		.amdhsa_fp16_overflow 0
		.amdhsa_tg_split 0
		.amdhsa_exception_fp_ieee_invalid_op 0
		.amdhsa_exception_fp_denorm_src 0
		.amdhsa_exception_fp_ieee_div_zero 0
		.amdhsa_exception_fp_ieee_overflow 0
		.amdhsa_exception_fp_ieee_underflow 0
		.amdhsa_exception_fp_ieee_inexact 0
		.amdhsa_exception_int_div_zero 0
	.end_amdhsa_kernel

amdhsa.kernels:
  - .agpr_count:     0
    .args:
      - .offset:         0
        .size:           208
        .value_kind:     by_value
      - .offset:         208
        .size:           4
        .value_kind:     hidden_block_count_x
      - .offset:         212
        .size:           4
        .value_kind:     hidden_block_count_y
      - .offset:         216
        .size:           4
        .value_kind:     hidden_block_count_z
      - .offset:         220
        .size:           2
        .value_kind:     hidden_group_size_x
      - .offset:         222
        .size:           2
        .value_kind:     hidden_group_size_y
      - .offset:         224
        .size:           2
        .value_kind:     hidden_group_size_z
      - .offset:         226
        .size:           2
        .value_kind:     hidden_remainder_x
      - .offset:         228
        .size:           2
        .value_kind:     hidden_remainder_y
      - .offset:         230
        .size:           2
        .value_kind:     hidden_remainder_z
      - .offset:         248
        .size:           8
        .value_kind:     hidden_global_offset_x
      - .offset:         256
        .size:           8
        .value_kind:     hidden_global_offset_y
      - .offset:         264
        .size:           8
        .value_kind:     hidden_global_offset_z
      - .offset:         272
        .size:           2
        .value_kind:     hidden_grid_dims
      - .offset:         328
        .size:           4
        .value_kind:     hidden_dynamic_lds_size
    .group_segment_fixed_size: 49408
    .kernarg_segment_align: 8
    .kernarg_segment_size: 464
    .language:       OpenCL C
    .language_version:
      - 2
      - 0
    .max_flat_workgroup_size: 512
    .name:           _Z11mega_kernel6Params
    .private_segment_fixed_size: 0
    .sgpr_count:     108
    .sgpr_spill_count: 85
    .symbol:         _Z11mega_kernel6Params.kd
    .uniform_work_group_size: 1
    .uses_dynamic_stack: false
    .vgpr_count:     248
    .vgpr_spill_count: 0
    .wavefront_size: 64
